# c1 plus non-temporal stores for the late-consumed gate sections (sig ratio / sig gB) in the W_in epilogue
# baseline (speedup 1.0000x reference)
; __device__ __forceinline__ unsigned cvt_pk_bf16(float lo, float hi) { unsigned r; asm volatile("v_cvt_pk_bf16_f32 %0, %1, %2" : "=v"(r) : "v"(lo), "v"(hi)); return r; }
;     __device__ __forceinline__ void operator()(const AccT& acc, const Unit& u, int wr, int wc, int fr, int fq) const {
;     ...
;         if (u.pn >= 40) {
;             const int ch0 = (u.pn - 40) * 128 + wc * 32 + 8 * fq;
;             f32x4 ba[2], bb[2];
; #pragma unroll
;             for (int n = 0; n < 2; ++n) { ba[n] = *(const f32x4*)(bias + 5 * D + ch0 + 4 * n); bb[n] = *(const f32x4*)(bias + 6 * D + ch0 + 4 * n); }
; #pragma unroll
;             for (int ai = 0; ai < 2; ++ai)
; #pragma unroll
;                 for (int m = 0; m < 4; ++m) { const int row = row0 + ai * 128 + m * 16;
;                     const float rstd = rs[ai * 4 + m];
;                     f32x4 rt[2], sb[2];
; #pragma unroll
;                     for (int n = 0; n < 2; ++n)
; #pragma unroll
;                         for (int j = 0; j < 4; ++j) { const float ea = __builtin_amdgcn_exp2f(-LOG2E * (acc[ai][0][m][n][j] * rstd + ba[n][j])), eb = __builtin_amdgcn_exp2f(-LOG2E * (acc[ai][1][m][n][j] * rstd + bb[n][j]));
;                             sb[n][j] = __builtin_amdgcn_rcpf(1.0f + eb); rt[n][j] = (1.0f + eb) * __builtin_amdgcn_rcpf(1.0f + ea); }
;                     u32x4 w; w.x = cvt_pk_bf16(rt[0][0], rt[0][1]); w.y = cvt_pk_bf16(rt[0][2], rt[0][3]); w.z = cvt_pk_bf16(rt[1][0], rt[1][1]); w.w = cvt_pk_bf16(rt[1][2], rt[1][3]);
;                     *(u32x4*)(Z + 5 * SEC + (size_t)row * D + ch0) = w;
.LBB0_125:
	s_andn2_b64 vcc, exec, s[16:17]
	s_cbranch_vccnz .LBB0_127
	v_lshl_add_u32 v0, s88, 7, v175
	v_lshlrev_b64 v[130:131], 2, v[0:1]
	v_lshl_add_u64 v[134:135], s[10:11], 0, v[130:131]
	v_lshl_add_u64 v[138:139], s[12:13], 0, v[130:131]
	global_load_dwordx4 v[130:133], v[134:135], off offset:16
	global_load_dwordx4 v[142:145], v[134:135], off
	s_nop 0
	global_load_dwordx4 v[134:137], v[138:139], off offset:16
	s_nop 0
	global_load_dwordx4 v[138:141], v[138:139], off
	s_mov_b64 s[16:17], 0x80000
	s_waitcnt vmcnt(0) lgkmcnt(0)
	v_fma_f32 v165, v126, v166, v142
	v_mul_f32_e32 v165, 0xbfb8aa3b, v165
	v_exp_f32_e32 v165, v165
	v_fma_f32 v168, v118, v166, v138
	v_mul_f32_e32 v168, 0xbfb8aa3b, v168
	v_exp_f32_e32 v168, v168
	v_add_f32_e32 v165, 1.0, v165
	v_rcp_f32_e32 v165, v165
	v_fma_f32 v169, v119, v166, v139
	v_add_f32_e32 v168, 1.0, v168
	v_rcp_f32_e32 v182, v168
	v_mul_f32_e32 v165, v165, v168
	v_fma_f32 v168, v127, v166, v143
	v_mul_f32_e32 v168, 0xbfb8aa3b, v168
	v_exp_f32_e32 v168, v168
	v_mul_f32_e32 v169, 0xbfb8aa3b, v169
	v_exp_f32_e32 v169, v169
	v_fma_f32 v170, v120, v166, v140
	v_add_f32_e32 v168, 1.0, v168
	v_rcp_f32_e32 v168, v168
	v_add_f32_e32 v169, 1.0, v169
	v_rcp_f32_e32 v183, v169
	v_mul_f32_e32 v170, 0xbfb8aa3b, v170
	v_mul_f32_e32 v168, v168, v169
	v_fma_f32 v169, v128, v166, v144
	v_mul_f32_e32 v169, 0xbfb8aa3b, v169
	v_exp_f32_e32 v169, v169
	v_exp_f32_e32 v170, v170
	v_fma_f32 v171, v121, v166, v141
	v_mul_f32_e32 v171, 0xbfb8aa3b, v171
	v_add_f32_e32 v169, 1.0, v169
	v_rcp_f32_e32 v169, v169
	v_add_f32_e32 v170, 1.0, v170
	v_rcp_f32_e32 v184, v170
	v_exp_f32_e32 v171, v171
	v_mul_f32_e32 v169, v169, v170
	v_fma_f32 v170, v129, v166, v145
	v_mul_f32_e32 v170, 0xbfb8aa3b, v170
	v_exp_f32_e32 v170, v170
	v_add_f32_e32 v171, 1.0, v171
	v_rcp_f32_e32 v185, v171
	v_fma_f32 v186, v114, v166, v134
	v_add_f32_e32 v170, 1.0, v170
	v_rcp_f32_e32 v170, v170
	v_mul_f32_e32 v186, 0xbfb8aa3b, v186
	v_exp_f32_e32 v186, v186
	v_fma_f32 v187, v115, v166, v135
	v_mul_f32_e32 v170, v170, v171
	v_fma_f32 v171, v122, v166, v130
	v_mul_f32_e32 v171, 0xbfb8aa3b, v171
	v_exp_f32_e32 v171, v171
	v_add_f32_e32 v186, 1.0, v186
	v_rcp_f32_e32 v192, v186
	v_mul_f32_e32 v187, 0xbfb8aa3b, v187
	v_add_f32_e32 v171, 1.0, v171
	v_rcp_f32_e32 v171, v171
	v_exp_f32_e32 v187, v187
	v_mul_f32_e32 v171, v171, v186
	v_fma_f32 v186, v123, v166, v131
	v_mul_f32_e32 v186, 0xbfb8aa3b, v186
	v_exp_f32_e32 v186, v186
	v_add_f32_e32 v187, 1.0, v187
	v_rcp_f32_e32 v193, v187
	v_add_f32_e32 v186, 1.0, v186
	v_rcp_f32_e32 v186, v186
	s_nop 0
	v_mul_f32_e32 v188, v186, v187
	v_fma_f32 v186, v124, v166, v132
	v_mul_f32_e32 v186, 0xbfb8aa3b, v186
	v_exp_f32_e32 v186, v186
	v_fma_f32 v187, v116, v166, v136
	v_mul_f32_e32 v187, 0xbfb8aa3b, v187
	v_exp_f32_e32 v187, v187
	v_add_f32_e32 v186, 1.0, v186
	v_rcp_f32_e32 v186, v186
	v_add_f32_e32 v187, 1.0, v187
	v_rcp_f32_e32 v194, v187
	v_mul_f32_e32 v189, v186, v187
	v_fma_f32 v186, v125, v166, v133
	v_mul_f32_e32 v186, 0xbfb8aa3b, v186
	v_exp_f32_e32 v186, v186
	v_fma_f32 v187, v117, v166, v137
	v_mul_f32_e32 v187, 0xbfb8aa3b, v187
	v_exp_f32_e32 v187, v187
	v_add_f32_e32 v186, 1.0, v186
	v_rcp_f32_e32 v186, v186
	v_add_f32_e32 v187, 1.0, v187
	v_rcp_f32_e32 v195, v187
	v_mul_f32_e32 v190, v186, v187
	v_cvt_pk_bf16_f32 v186, v165, v168
	v_cvt_pk_bf16_f32 v187, v169, v170
	v_lshlrev_b64 v[168:169], 1, v[0:1]
	v_fma_f32 v0, v110, v167, v142
	v_mul_f32_e32 v0, 0xbfb8aa3b, v0
	v_exp_f32_e32 v0, v0
	v_ashrrev_i32_e32 v165, 31, v164
	v_cvt_pk_bf16_f32 v188, v171, v188
	v_lshlrev_b64 v[170:171], 12, v[164:165]
	v_fma_f32 v165, v102, v167, v138
	v_mul_f32_e32 v165, 0xbfb8aa3b, v165
	v_exp_f32_e32 v165, v165
	v_add_f32_e32 v0, 1.0, v0
	v_rcp_f32_e32 v0, v0
	v_cvt_pk_bf16_f32 v189, v189, v190
	v_lshl_add_u64 v[190:191], s[14:15], 0, v[170:171]
	v_lshl_add_u64 v[190:191], v[190:191], 0, v[168:169]
	v_add_f32_e32 v165, 1.0, v165
	global_store_dwordx4 v[190:191], v[186:189], off nt
	v_rcp_f32_e32 v190, v165
	v_mul_f32_e32 v0, v0, v165
	v_fma_f32 v165, v111, v167, v143
	v_mul_f32_e32 v165, 0xbfb8aa3b, v165
	v_lshl_add_u64 v[186:187], s[18:19], 0, v[170:171]
	v_exp_f32_e32 v165, v165
	v_cvt_pk_bf16_f32 v182, v182, v183
	v_lshl_add_u64 v[186:187], v[186:187], 0, v[168:169]
	v_cvt_pk_bf16_f32 v183, v184, v185
	v_cvt_pk_bf16_f32 v184, v192, v193
	v_cvt_pk_bf16_f32 v185, v194, v195
	global_store_dwordx4 v[186:187], v[182:185], off nt
	v_add_f32_e32 v165, 1.0, v165
	v_rcp_f32_e32 v165, v165
	v_fma_f32 v182, v103, v167, v139
	v_mul_f32_e32 v182, 0xbfb8aa3b, v182
	v_exp_f32_e32 v182, v182
	v_fma_f32 v183, v104, v167, v140
	v_mul_f32_e32 v183, 0xbfb8aa3b, v183
	v_exp_f32_e32 v183, v183
	v_add_f32_e32 v182, 1.0, v182
	v_rcp_f32_e32 v191, v182
	v_mul_f32_e32 v165, v165, v182
	v_fma_f32 v182, v112, v167, v144
	v_mul_f32_e32 v182, 0xbfb8aa3b, v182
	v_exp_f32_e32 v182, v182
	v_add_f32_e32 v183, 1.0, v183
	v_rcp_f32_e32 v192, v183
	v_fma_f32 v184, v105, v167, v141
	v_add_f32_e32 v182, 1.0, v182
	v_rcp_f32_e32 v182, v182
	v_mul_f32_e32 v184, 0xbfb8aa3b, v184
	v_exp_f32_e32 v184, v184
	v_fma_f32 v185, v98, v167, v134
	v_mul_f32_e32 v183, v182, v183
	v_fma_f32 v182, v113, v167, v145
	v_mul_f32_e32 v182, 0xbfb8aa3b, v182
	v_exp_f32_e32 v182, v182
	v_add_f32_e32 v184, 1.0, v184
	v_rcp_f32_e32 v193, v184
	v_mul_f32_e32 v185, 0xbfb8aa3b, v185
	v_add_f32_e32 v182, 1.0, v182
	v_rcp_f32_e32 v182, v182
	v_exp_f32_e32 v185, v185
	v_fma_f32 v186, v99, v167, v135
	v_mul_f32_e32 v186, 0xbfb8aa3b, v186
	v_mul_f32_e32 v184, v182, v184
	v_fma_f32 v182, v106, v167, v130
	v_mul_f32_e32 v182, 0xbfb8aa3b, v182
	v_exp_f32_e32 v182, v182
	v_add_f32_e32 v185, 1.0, v185
; __device__ __forceinline__ unsigned cvt_pk_bf16(float lo, float hi) { unsigned r; asm volatile("v_cvt_pk_bf16_f32 %0, %1, %2" : "=v"(r) : "v"(lo), "v"(hi)); return r; }
;     __device__ __forceinline__ void operator()(const AccT& acc, const Unit& u, int wr, int wc, int fr, int fq) const {
;     ...
;             for (int ai = 0; ai < 2; ++ai)
; #pragma unroll
;                 for (int m = 0; m < 4; ++m) { const int row = row0 + ai * 128 + m * 16;
;                     const float rstd = rs[ai * 4 + m];
;                     f32x4 rt[2], sb[2];
; #pragma unroll
;                     for (int n = 0; n < 2; ++n)
; #pragma unroll
;                         for (int j = 0; j < 4; ++j) { const float ea = __builtin_amdgcn_exp2f(-LOG2E * (acc[ai][0][m][n][j] * rstd + ba[n][j])), eb = __builtin_amdgcn_exp2f(-LOG2E * (acc[ai][1][m][n][j] * rstd + bb[n][j]));
;                             sb[n][j] = __builtin_amdgcn_rcpf(1.0f + eb); rt[n][j] = (1.0f + eb) * __builtin_amdgcn_rcpf(1.0f + ea); }
;                     u32x4 w; w.x = cvt_pk_bf16(rt[0][0], rt[0][1]); w.y = cvt_pk_bf16(rt[0][2], rt[0][3]); w.z = cvt_pk_bf16(rt[1][0], rt[1][1]); w.w = cvt_pk_bf16(rt[1][2], rt[1][3]);
;                     *(u32x4*)(Z + 5 * SEC + (size_t)row * D + ch0) = w;
;                     u32x4 v; v.x = cvt_pk_bf16(sb[0][0], sb[0][1]); v.y = cvt_pk_bf16(sb[0][2], sb[0][3]); v.z = cvt_pk_bf16(sb[1][0], sb[1][1]); v.w = cvt_pk_bf16(sb[1][2], sb[1][3]);
;                     *(u32x4*)(Z + 6 * SEC + (size_t)row * D + ch0) = v; }
	v_rcp_f32_e32 v194, v185
	v_exp_f32_e32 v186, v186
	v_add_f32_e32 v182, 1.0, v182
	v_rcp_f32_e32 v182, v182
	v_add_f32_e32 v186, 1.0, v186
	v_rcp_f32_e32 v195, v186
	v_mul_f32_e32 v185, v182, v185
	v_fma_f32 v182, v107, v167, v131
	v_mul_f32_e32 v182, 0xbfb8aa3b, v182
	v_exp_f32_e32 v182, v182
	s_nop 0
	v_add_f32_e32 v182, 1.0, v182
	v_rcp_f32_e32 v182, v182
	s_nop 0
	v_mul_f32_e32 v187, v182, v186
	v_fma_f32 v182, v108, v167, v132
	v_mul_f32_e32 v182, 0xbfb8aa3b, v182
	v_exp_f32_e32 v182, v182
	v_fma_f32 v186, v100, v167, v136
	v_mul_f32_e32 v186, 0xbfb8aa3b, v186
	v_exp_f32_e32 v186, v186
	v_add_f32_e32 v182, 1.0, v182
	v_rcp_f32_e32 v182, v182
	v_add_f32_e32 v186, 1.0, v186
	v_rcp_f32_e32 v196, v186
	v_mul_f32_e32 v188, v182, v186
	v_fma_f32 v182, v109, v167, v133
	v_mul_f32_e32 v182, 0xbfb8aa3b, v182
	v_exp_f32_e32 v182, v182
	v_fma_f32 v186, v101, v167, v137
	v_mul_f32_e32 v186, 0xbfb8aa3b, v186
	v_exp_f32_e32 v186, v186
	v_add_f32_e32 v182, 1.0, v182
	v_rcp_f32_e32 v182, v182
	v_add_f32_e32 v186, 1.0, v186
	v_rcp_f32_e32 v197, v186
	v_mul_f32_e32 v189, v182, v186
	v_cvt_pk_bf16_f32 v182, v0, v165
	v_fma_f32 v0, v94, v162, v142
	v_mul_f32_e32 v0, 0xbfb8aa3b, v0
	v_exp_f32_e32 v0, v0
	v_fma_f32 v165, v86, v162, v138
	v_mul_f32_e32 v165, 0xbfb8aa3b, v165
	v_or_b32_e32 v186, 16, v164
	v_exp_f32_e32 v165, v165
	v_add_f32_e32 v0, 1.0, v0
	v_cvt_pk_bf16_f32 v183, v183, v184
	v_cvt_pk_bf16_f32 v184, v185, v187
	v_ashrrev_i32_e32 v187, 31, v186
	v_rcp_f32_e32 v0, v0
	v_lshlrev_b64 v[186:187], 12, v[186:187]
	v_cvt_pk_bf16_f32 v185, v188, v189
	v_lshl_add_u64 v[188:189], s[14:15], 0, v[186:187]
	v_lshl_add_u64 v[188:189], v[188:189], 0, v[168:169]
	v_add_f32_e32 v165, 1.0, v165
	global_store_dwordx4 v[188:189], v[182:185], off nt
	v_mul_f32_e32 v0, v0, v165
	v_lshl_add_u64 v[186:187], s[18:19], 0, v[186:187]
	v_cvt_pk_bf16_f32 v182, v190, v191
	v_rcp_f32_e32 v190, v165
	v_fma_f32 v165, v95, v162, v143
	v_mul_f32_e32 v165, 0xbfb8aa3b, v165
	v_exp_f32_e32 v165, v165
	v_lshl_add_u64 v[186:187], v[186:187], 0, v[168:169]
	v_cvt_pk_bf16_f32 v183, v192, v193
	v_cvt_pk_bf16_f32 v184, v194, v195
	v_cvt_pk_bf16_f32 v185, v196, v197
	global_store_dwordx4 v[186:187], v[182:185], off nt
	v_add_f32_e32 v165, 1.0, v165
	v_rcp_f32_e32 v165, v165
	v_fma_f32 v182, v87, v162, v139
	v_mul_f32_e32 v182, 0xbfb8aa3b, v182
	v_exp_f32_e32 v182, v182
	v_fma_f32 v183, v88, v162, v140
	v_mul_f32_e32 v183, 0xbfb8aa3b, v183
	v_exp_f32_e32 v183, v183
	v_add_f32_e32 v182, 1.0, v182
	v_rcp_f32_e32 v191, v182
	v_mul_f32_e32 v165, v165, v182
	v_fma_f32 v182, v96, v162, v144
	v_mul_f32_e32 v182, 0xbfb8aa3b, v182
	v_exp_f32_e32 v182, v182
	v_add_f32_e32 v183, 1.0, v183
	v_rcp_f32_e32 v192, v183
	v_fma_f32 v184, v89, v162, v141
	v_add_f32_e32 v182, 1.0, v182
	v_rcp_f32_e32 v182, v182
	v_mul_f32_e32 v184, 0xbfb8aa3b, v184
	v_exp_f32_e32 v184, v184
	v_fma_f32 v185, v82, v162, v134
	v_mul_f32_e32 v183, v182, v183
	v_fma_f32 v182, v97, v162, v145
	v_mul_f32_e32 v182, 0xbfb8aa3b, v182
	v_exp_f32_e32 v182, v182
	v_add_f32_e32 v184, 1.0, v184
	v_rcp_f32_e32 v193, v184
	v_mul_f32_e32 v185, 0xbfb8aa3b, v185
	v_add_f32_e32 v182, 1.0, v182
	v_rcp_f32_e32 v182, v182
	v_exp_f32_e32 v185, v185
	v_fma_f32 v186, v83, v162, v135
	v_mul_f32_e32 v186, 0xbfb8aa3b, v186
	v_mul_f32_e32 v184, v182, v184
	v_fma_f32 v182, v90, v162, v130
	v_mul_f32_e32 v182, 0xbfb8aa3b, v182
	v_exp_f32_e32 v182, v182
	v_add_f32_e32 v185, 1.0, v185
	v_rcp_f32_e32 v194, v185
	v_exp_f32_e32 v186, v186
	v_add_f32_e32 v182, 1.0, v182
	v_rcp_f32_e32 v182, v182
	v_add_f32_e32 v186, 1.0, v186
	v_rcp_f32_e32 v195, v186
	v_mul_f32_e32 v185, v182, v185
	v_fma_f32 v182, v91, v162, v131
	v_mul_f32_e32 v182, 0xbfb8aa3b, v182
	v_exp_f32_e32 v182, v182
	s_nop 0
	v_add_f32_e32 v182, 1.0, v182
	v_rcp_f32_e32 v182, v182
	s_nop 0
	v_mul_f32_e32 v187, v182, v186
	v_fma_f32 v182, v92, v162, v132
	v_mul_f32_e32 v182, 0xbfb8aa3b, v182
	v_exp_f32_e32 v182, v182
	v_fma_f32 v186, v84, v162, v136
	v_mul_f32_e32 v186, 0xbfb8aa3b, v186
	v_exp_f32_e32 v186, v186
	v_add_f32_e32 v182, 1.0, v182
	v_rcp_f32_e32 v182, v182
	v_add_f32_e32 v186, 1.0, v186
	v_rcp_f32_e32 v196, v186
	v_mul_f32_e32 v188, v182, v186
	v_fma_f32 v182, v93, v162, v133
	v_mul_f32_e32 v182, 0xbfb8aa3b, v182
	v_exp_f32_e32 v182, v182
	v_fma_f32 v186, v85, v162, v137
	v_mul_f32_e32 v186, 0xbfb8aa3b, v186
	v_exp_f32_e32 v186, v186
	v_add_f32_e32 v182, 1.0, v182
	v_rcp_f32_e32 v182, v182
	v_add_f32_e32 v186, 1.0, v186
	v_rcp_f32_e32 v197, v186
	v_mul_f32_e32 v189, v182, v186
	v_cvt_pk_bf16_f32 v182, v0, v165
	v_fma_f32 v0, v78, v163, v142
	v_mul_f32_e32 v0, 0xbfb8aa3b, v0
	v_exp_f32_e32 v0, v0
	v_fma_f32 v165, v70, v163, v138
	v_mul_f32_e32 v165, 0xbfb8aa3b, v165
	v_or_b32_e32 v186, 32, v164
	v_exp_f32_e32 v165, v165
	v_add_f32_e32 v0, 1.0, v0
	v_cvt_pk_bf16_f32 v183, v183, v184
	v_cvt_pk_bf16_f32 v184, v185, v187
	v_ashrrev_i32_e32 v187, 31, v186
	v_rcp_f32_e32 v0, v0
	v_lshlrev_b64 v[186:187], 12, v[186:187]
	v_cvt_pk_bf16_f32 v185, v188, v189
	v_lshl_add_u64 v[188:189], s[14:15], 0, v[186:187]
	v_lshl_add_u64 v[188:189], v[188:189], 0, v[168:169]
	v_add_f32_e32 v165, 1.0, v165
	global_store_dwordx4 v[188:189], v[182:185], off nt
	v_mul_f32_e32 v0, v0, v165
	v_lshl_add_u64 v[186:187], s[18:19], 0, v[186:187]
	v_cvt_pk_bf16_f32 v182, v190, v191
	v_rcp_f32_e32 v190, v165
	v_fma_f32 v165, v79, v163, v143
	v_mul_f32_e32 v165, 0xbfb8aa3b, v165
	v_exp_f32_e32 v165, v165
	v_lshl_add_u64 v[186:187], v[186:187], 0, v[168:169]
	v_cvt_pk_bf16_f32 v183, v192, v193
	v_cvt_pk_bf16_f32 v184, v194, v195
	v_cvt_pk_bf16_f32 v185, v196, v197
	global_store_dwordx4 v[186:187], v[182:185], off nt
; __device__ __forceinline__ unsigned cvt_pk_bf16(float lo, float hi) { unsigned r; asm volatile("v_cvt_pk_bf16_f32 %0, %1, %2" : "=v"(r) : "v"(lo), "v"(hi)); return r; }
;     __device__ __forceinline__ void operator()(const AccT& acc, const Unit& u, int wr, int wc, int fr, int fq) const {
;     ...
;             for (int ai = 0; ai < 2; ++ai)
; #pragma unroll
;                 for (int m = 0; m < 4; ++m) { const int row = row0 + ai * 128 + m * 16;
;                     const float rstd = rs[ai * 4 + m];
;                     f32x4 rt[2], sb[2];
; #pragma unroll
;                     for (int n = 0; n < 2; ++n)
; #pragma unroll
;                         for (int j = 0; j < 4; ++j) { const float ea = __builtin_amdgcn_exp2f(-LOG2E * (acc[ai][0][m][n][j] * rstd + ba[n][j])), eb = __builtin_amdgcn_exp2f(-LOG2E * (acc[ai][1][m][n][j] * rstd + bb[n][j]));
;                             sb[n][j] = __builtin_amdgcn_rcpf(1.0f + eb); rt[n][j] = (1.0f + eb) * __builtin_amdgcn_rcpf(1.0f + ea); }
;                     u32x4 w; w.x = cvt_pk_bf16(rt[0][0], rt[0][1]); w.y = cvt_pk_bf16(rt[0][2], rt[0][3]); w.z = cvt_pk_bf16(rt[1][0], rt[1][1]); w.w = cvt_pk_bf16(rt[1][2], rt[1][3]);
;                     *(u32x4*)(Z + 5 * SEC + (size_t)row * D + ch0) = w;
;                     u32x4 v; v.x = cvt_pk_bf16(sb[0][0], sb[0][1]); v.y = cvt_pk_bf16(sb[0][2], sb[0][3]); v.z = cvt_pk_bf16(sb[1][0], sb[1][1]); v.w = cvt_pk_bf16(sb[1][2], sb[1][3]);
;                     *(u32x4*)(Z + 6 * SEC + (size_t)row * D + ch0) = v; }
	v_add_f32_e32 v165, 1.0, v165
	v_rcp_f32_e32 v165, v165
	v_fma_f32 v182, v71, v163, v139
	v_mul_f32_e32 v182, 0xbfb8aa3b, v182
	v_exp_f32_e32 v182, v182
	v_fma_f32 v183, v72, v163, v140
	v_mul_f32_e32 v183, 0xbfb8aa3b, v183
	v_exp_f32_e32 v183, v183
	v_add_f32_e32 v182, 1.0, v182
	v_rcp_f32_e32 v191, v182
	v_mul_f32_e32 v165, v165, v182
	v_fma_f32 v182, v80, v163, v144
	v_mul_f32_e32 v182, 0xbfb8aa3b, v182
	v_exp_f32_e32 v182, v182
	v_add_f32_e32 v183, 1.0, v183
	v_rcp_f32_e32 v192, v183
	v_fma_f32 v184, v73, v163, v141
	v_add_f32_e32 v182, 1.0, v182
	v_rcp_f32_e32 v182, v182
	v_mul_f32_e32 v184, 0xbfb8aa3b, v184
	v_exp_f32_e32 v184, v184
	v_fma_f32 v185, v66, v163, v134
	v_mul_f32_e32 v183, v182, v183
	v_fma_f32 v182, v81, v163, v145
	v_mul_f32_e32 v182, 0xbfb8aa3b, v182
	v_exp_f32_e32 v182, v182
	v_add_f32_e32 v184, 1.0, v184
	v_rcp_f32_e32 v193, v184
	v_mul_f32_e32 v185, 0xbfb8aa3b, v185
	v_add_f32_e32 v182, 1.0, v182
	v_rcp_f32_e32 v182, v182
	v_exp_f32_e32 v185, v185
	v_fma_f32 v186, v67, v163, v135
	v_mul_f32_e32 v186, 0xbfb8aa3b, v186
	v_mul_f32_e32 v184, v182, v184
	v_fma_f32 v182, v74, v163, v130
	v_mul_f32_e32 v182, 0xbfb8aa3b, v182
	v_exp_f32_e32 v182, v182
	v_add_f32_e32 v185, 1.0, v185
	v_rcp_f32_e32 v194, v185
	v_exp_f32_e32 v186, v186
	v_add_f32_e32 v182, 1.0, v182
	v_rcp_f32_e32 v182, v182
	v_add_f32_e32 v186, 1.0, v186
	v_rcp_f32_e32 v195, v186
	v_mul_f32_e32 v185, v182, v185
	v_fma_f32 v182, v75, v163, v131
	v_mul_f32_e32 v182, 0xbfb8aa3b, v182
	v_exp_f32_e32 v182, v182
	s_nop 0
	v_add_f32_e32 v182, 1.0, v182
	v_rcp_f32_e32 v182, v182
	s_nop 0
	v_mul_f32_e32 v187, v182, v186
	v_fma_f32 v182, v76, v163, v132
	v_mul_f32_e32 v182, 0xbfb8aa3b, v182
	v_exp_f32_e32 v182, v182
	v_fma_f32 v186, v68, v163, v136
	v_mul_f32_e32 v186, 0xbfb8aa3b, v186
	v_exp_f32_e32 v186, v186
	v_add_f32_e32 v182, 1.0, v182
	v_rcp_f32_e32 v182, v182
	v_add_f32_e32 v186, 1.0, v186
	v_rcp_f32_e32 v196, v186
	v_mul_f32_e32 v188, v182, v186
	v_fma_f32 v182, v77, v163, v133
	v_mul_f32_e32 v182, 0xbfb8aa3b, v182
	v_exp_f32_e32 v182, v182
	v_fma_f32 v186, v69, v163, v137
	v_mul_f32_e32 v186, 0xbfb8aa3b, v186
	v_exp_f32_e32 v186, v186
	v_add_f32_e32 v182, 1.0, v182
	v_rcp_f32_e32 v182, v182
	v_add_f32_e32 v186, 1.0, v186
	v_rcp_f32_e32 v197, v186
	v_mul_f32_e32 v189, v182, v186
	v_cvt_pk_bf16_f32 v182, v0, v165
	v_fma_f32 v0, v62, v160, v142
	v_mul_f32_e32 v0, 0xbfb8aa3b, v0
	v_exp_f32_e32 v0, v0
	v_fma_f32 v165, v54, v160, v138
	v_mul_f32_e32 v165, 0xbfb8aa3b, v165
	v_or_b32_e32 v186, 48, v164
	v_exp_f32_e32 v165, v165
	v_add_f32_e32 v0, 1.0, v0
	v_cvt_pk_bf16_f32 v183, v183, v184
	v_cvt_pk_bf16_f32 v184, v185, v187
	v_ashrrev_i32_e32 v187, 31, v186
	v_rcp_f32_e32 v0, v0
	v_lshlrev_b64 v[186:187], 12, v[186:187]
	v_cvt_pk_bf16_f32 v185, v188, v189
	v_lshl_add_u64 v[188:189], s[14:15], 0, v[186:187]
	v_lshl_add_u64 v[188:189], v[188:189], 0, v[168:169]
	v_add_f32_e32 v165, 1.0, v165
	global_store_dwordx4 v[188:189], v[182:185], off nt
	v_mul_f32_e32 v0, v0, v165
	v_lshl_add_u64 v[186:187], s[18:19], 0, v[186:187]
	v_cvt_pk_bf16_f32 v182, v190, v191
	v_rcp_f32_e32 v190, v165
	v_fma_f32 v165, v63, v160, v143
	v_mul_f32_e32 v165, 0xbfb8aa3b, v165
	v_exp_f32_e32 v165, v165
	v_lshl_add_u64 v[186:187], v[186:187], 0, v[168:169]
	v_cvt_pk_bf16_f32 v183, v192, v193
	v_cvt_pk_bf16_f32 v184, v194, v195
	v_cvt_pk_bf16_f32 v185, v196, v197
	global_store_dwordx4 v[186:187], v[182:185], off nt
	v_add_f32_e32 v165, 1.0, v165
	v_rcp_f32_e32 v165, v165
	v_fma_f32 v182, v55, v160, v139
	v_mul_f32_e32 v182, 0xbfb8aa3b, v182
	v_exp_f32_e32 v182, v182
	v_fma_f32 v183, v56, v160, v140
	v_mul_f32_e32 v183, 0xbfb8aa3b, v183
	v_exp_f32_e32 v183, v183
	v_add_f32_e32 v182, 1.0, v182
	v_rcp_f32_e32 v191, v182
	v_mul_f32_e32 v165, v165, v182
	v_fma_f32 v182, v64, v160, v144
	v_mul_f32_e32 v182, 0xbfb8aa3b, v182
	v_exp_f32_e32 v182, v182
	v_add_f32_e32 v183, 1.0, v183
	v_rcp_f32_e32 v192, v183
	v_fma_f32 v184, v57, v160, v141
	v_add_f32_e32 v182, 1.0, v182
	v_rcp_f32_e32 v182, v182
	v_mul_f32_e32 v184, 0xbfb8aa3b, v184
	v_exp_f32_e32 v184, v184
	v_fma_f32 v185, v50, v160, v134
	v_mul_f32_e32 v183, v182, v183
	v_fma_f32 v182, v65, v160, v145
	v_mul_f32_e32 v182, 0xbfb8aa3b, v182
	v_exp_f32_e32 v182, v182
	v_add_f32_e32 v184, 1.0, v184
	v_rcp_f32_e32 v193, v184
	v_mul_f32_e32 v185, 0xbfb8aa3b, v185
	v_add_f32_e32 v182, 1.0, v182
	v_rcp_f32_e32 v182, v182
	v_exp_f32_e32 v185, v185
	v_fma_f32 v186, v51, v160, v135
	v_mul_f32_e32 v186, 0xbfb8aa3b, v186
	v_mul_f32_e32 v184, v182, v184
	v_fma_f32 v182, v58, v160, v130
	v_mul_f32_e32 v182, 0xbfb8aa3b, v182
	v_exp_f32_e32 v182, v182
	v_add_f32_e32 v185, 1.0, v185
	v_rcp_f32_e32 v194, v185
	v_exp_f32_e32 v186, v186
	v_add_f32_e32 v182, 1.0, v182
	v_rcp_f32_e32 v182, v182
	v_fma_f32 v187, v52, v160, v136
	v_add_f32_e32 v186, 1.0, v186
	v_rcp_f32_e32 v195, v186
	v_mul_f32_e32 v185, v182, v185
	v_fma_f32 v182, v59, v160, v131
	v_mul_f32_e32 v182, 0xbfb8aa3b, v182
	v_exp_f32_e32 v182, v182
	v_mul_f32_e32 v187, 0xbfb8aa3b, v187
	v_exp_f32_e32 v187, v187
	v_fma_f32 v188, v53, v160, v137
	v_add_f32_e32 v182, 1.0, v182
	v_rcp_f32_e32 v182, v182
	v_add_f32_e32 v187, 1.0, v187
	v_rcp_f32_e32 v196, v187
	v_mul_f32_e32 v188, 0xbfb8aa3b, v188
	v_mul_f32_e32 v186, v182, v186
	v_fma_f32 v182, v60, v160, v132
	v_mul_f32_e32 v182, 0xbfb8aa3b, v182
	v_exp_f32_e32 v182, v182
	v_exp_f32_e32 v188, v188
	v_add_f32_e32 v182, 1.0, v182
	v_rcp_f32_e32 v182, v182
	v_add_f32_e32 v188, 1.0, v188
	v_rcp_f32_e32 v197, v188
	v_mul_f32_e32 v187, v182, v187
	v_fma_f32 v182, v61, v160, v133
	v_mul_f32_e32 v182, 0xbfb8aa3b, v182
	v_exp_f32_e32 v182, v182
	s_nop 0
; __device__ __forceinline__ unsigned cvt_pk_bf16(float lo, float hi) { unsigned r; asm volatile("v_cvt_pk_bf16_f32 %0, %1, %2" : "=v"(r) : "v"(lo), "v"(hi)); return r; }
;     __device__ __forceinline__ void operator()(const AccT& acc, const Unit& u, int wr, int wc, int fr, int fq) const {
;     ...
;             for (int ai = 0; ai < 2; ++ai)
; #pragma unroll
;                 for (int m = 0; m < 4; ++m) { const int row = row0 + ai * 128 + m * 16;
;                     const float rstd = rs[ai * 4 + m];
;                     f32x4 rt[2], sb[2];
; #pragma unroll
;                     for (int n = 0; n < 2; ++n)
; #pragma unroll
;                         for (int j = 0; j < 4; ++j) { const float ea = __builtin_amdgcn_exp2f(-LOG2E * (acc[ai][0][m][n][j] * rstd + ba[n][j])), eb = __builtin_amdgcn_exp2f(-LOG2E * (acc[ai][1][m][n][j] * rstd + bb[n][j]));
;                             sb[n][j] = __builtin_amdgcn_rcpf(1.0f + eb); rt[n][j] = (1.0f + eb) * __builtin_amdgcn_rcpf(1.0f + ea); }
;                     u32x4 w; w.x = cvt_pk_bf16(rt[0][0], rt[0][1]); w.y = cvt_pk_bf16(rt[0][2], rt[0][3]); w.z = cvt_pk_bf16(rt[1][0], rt[1][1]); w.w = cvt_pk_bf16(rt[1][2], rt[1][3]);
;                     *(u32x4*)(Z + 5 * SEC + (size_t)row * D + ch0) = w;
;                     u32x4 v; v.x = cvt_pk_bf16(sb[0][0], sb[0][1]); v.y = cvt_pk_bf16(sb[0][2], sb[0][3]); v.z = cvt_pk_bf16(sb[1][0], sb[1][1]); v.w = cvt_pk_bf16(sb[1][2], sb[1][3]);
;                     *(u32x4*)(Z + 6 * SEC + (size_t)row * D + ch0) = v; }
	v_add_f32_e32 v182, 1.0, v182
	v_rcp_f32_e32 v182, v182
	s_nop 0
	v_mul_f32_e32 v188, v182, v188
	v_cvt_pk_bf16_f32 v182, v0, v165
	v_fma_f32 v0, v46, v161, v142
	v_mul_f32_e32 v0, 0xbfb8aa3b, v0
	v_exp_f32_e32 v0, v0
	v_fma_f32 v165, v38, v161, v138
	v_mul_f32_e32 v165, 0xbfb8aa3b, v165
	v_exp_f32_e32 v165, v165
	v_add_f32_e32 v0, 1.0, v0
	v_rcp_f32_e32 v0, v0
	v_cvt_pk_bf16_f32 v183, v183, v184
	v_cvt_pk_bf16_f32 v184, v185, v186
	v_cvt_pk_bf16_f32 v185, v187, v188
	v_lshl_add_u64 v[186:187], v[170:171], 0, s[16:17]
	v_lshl_add_u64 v[188:189], s[14:15], 0, v[186:187]
	v_lshl_add_u64 v[188:189], v[188:189], 0, v[168:169]
	v_add_f32_e32 v165, 1.0, v165
	global_store_dwordx4 v[188:189], v[182:185], off nt
	v_mul_f32_e32 v0, v0, v165
	v_lshl_add_u64 v[186:187], s[18:19], 0, v[186:187]
	v_cvt_pk_bf16_f32 v182, v190, v191
	v_rcp_f32_e32 v190, v165
	v_fma_f32 v165, v47, v161, v143
	v_mul_f32_e32 v165, 0xbfb8aa3b, v165
	v_exp_f32_e32 v165, v165
	v_lshl_add_u64 v[186:187], v[186:187], 0, v[168:169]
	v_cvt_pk_bf16_f32 v183, v192, v193
	v_cvt_pk_bf16_f32 v184, v194, v195
	v_cvt_pk_bf16_f32 v185, v196, v197
	global_store_dwordx4 v[186:187], v[182:185], off nt
	v_add_f32_e32 v165, 1.0, v165
	v_rcp_f32_e32 v165, v165
	v_fma_f32 v182, v39, v161, v139
	v_mul_f32_e32 v182, 0xbfb8aa3b, v182
	v_exp_f32_e32 v182, v182
	v_fma_f32 v183, v40, v161, v140
	v_mul_f32_e32 v183, 0xbfb8aa3b, v183
	v_exp_f32_e32 v183, v183
	v_add_f32_e32 v182, 1.0, v182
	v_rcp_f32_e32 v191, v182
	v_mul_f32_e32 v165, v165, v182
	v_fma_f32 v182, v48, v161, v144
	v_mul_f32_e32 v182, 0xbfb8aa3b, v182
	v_exp_f32_e32 v182, v182
	v_add_f32_e32 v183, 1.0, v183
	v_rcp_f32_e32 v192, v183
	v_fma_f32 v184, v41, v161, v141
	v_add_f32_e32 v182, 1.0, v182
	v_rcp_f32_e32 v182, v182
	v_mul_f32_e32 v184, 0xbfb8aa3b, v184
	v_exp_f32_e32 v184, v184
	v_fma_f32 v185, v34, v161, v134
	v_mul_f32_e32 v183, v182, v183
	v_fma_f32 v182, v49, v161, v145
	v_mul_f32_e32 v182, 0xbfb8aa3b, v182
	v_exp_f32_e32 v182, v182
	v_add_f32_e32 v184, 1.0, v184
	v_rcp_f32_e32 v193, v184
	v_mul_f32_e32 v185, 0xbfb8aa3b, v185
	v_add_f32_e32 v182, 1.0, v182
	v_rcp_f32_e32 v182, v182
	v_exp_f32_e32 v185, v185
	v_fma_f32 v186, v35, v161, v135
	v_mul_f32_e32 v186, 0xbfb8aa3b, v186
	v_mul_f32_e32 v184, v182, v184
	v_fma_f32 v182, v42, v161, v130
	v_mul_f32_e32 v182, 0xbfb8aa3b, v182
	v_exp_f32_e32 v182, v182
	v_add_f32_e32 v185, 1.0, v185
	v_rcp_f32_e32 v194, v185
	v_exp_f32_e32 v186, v186
	v_add_f32_e32 v182, 1.0, v182
	v_rcp_f32_e32 v182, v182
	v_fma_f32 v187, v36, v161, v136
	v_add_f32_e32 v186, 1.0, v186
	v_rcp_f32_e32 v195, v186
	v_mul_f32_e32 v185, v182, v185
	v_fma_f32 v182, v43, v161, v131
	v_mul_f32_e32 v182, 0xbfb8aa3b, v182
	v_exp_f32_e32 v182, v182
	v_mul_f32_e32 v187, 0xbfb8aa3b, v187
	v_exp_f32_e32 v187, v187
	v_fma_f32 v188, v37, v161, v137
	v_add_f32_e32 v182, 1.0, v182
	v_rcp_f32_e32 v182, v182
	v_add_f32_e32 v187, 1.0, v187
	v_rcp_f32_e32 v196, v187
	v_mul_f32_e32 v188, 0xbfb8aa3b, v188
	v_mul_f32_e32 v186, v182, v186
	v_fma_f32 v182, v44, v161, v132
	v_mul_f32_e32 v182, 0xbfb8aa3b, v182
	v_exp_f32_e32 v182, v182
	v_exp_f32_e32 v188, v188
	v_add_f32_e32 v182, 1.0, v182
	v_rcp_f32_e32 v182, v182
	v_add_f32_e32 v188, 1.0, v188
	v_rcp_f32_e32 v197, v188
	v_mul_f32_e32 v187, v182, v187
	v_fma_f32 v182, v45, v161, v133
	v_mul_f32_e32 v182, 0xbfb8aa3b, v182
	v_exp_f32_e32 v182, v182
	s_nop 0
	v_add_f32_e32 v182, 1.0, v182
	v_rcp_f32_e32 v182, v182
	s_nop 0
	v_mul_f32_e32 v188, v182, v188
	v_cvt_pk_bf16_f32 v182, v0, v165
	v_fma_f32 v0, v30, v158, v142
	v_mul_f32_e32 v0, 0xbfb8aa3b, v0
	v_exp_f32_e32 v0, v0
	v_fma_f32 v165, v22, v158, v138
	v_mul_f32_e32 v165, 0xbfb8aa3b, v165
	v_exp_f32_e32 v165, v165
	v_add_f32_e32 v0, 1.0, v0
	v_rcp_f32_e32 v0, v0
	v_cvt_pk_bf16_f32 v183, v183, v184
	v_cvt_pk_bf16_f32 v184, v185, v186
	v_cvt_pk_bf16_f32 v185, v187, v188
	v_lshl_add_u64 v[186:187], v[170:171], 0, s[58:59]
	v_lshl_add_u64 v[188:189], s[14:15], 0, v[186:187]
	v_lshl_add_u64 v[188:189], v[188:189], 0, v[168:169]
	v_add_f32_e32 v165, 1.0, v165
	global_store_dwordx4 v[188:189], v[182:185], off nt
	v_mul_f32_e32 v0, v0, v165
	v_lshl_add_u64 v[186:187], s[18:19], 0, v[186:187]
	v_cvt_pk_bf16_f32 v182, v190, v191
	v_rcp_f32_e32 v190, v165
	v_fma_f32 v165, v31, v158, v143
	v_mul_f32_e32 v165, 0xbfb8aa3b, v165
	v_exp_f32_e32 v165, v165
	v_lshl_add_u64 v[186:187], v[186:187], 0, v[168:169]
	v_cvt_pk_bf16_f32 v183, v192, v193
	v_cvt_pk_bf16_f32 v184, v194, v195
	v_cvt_pk_bf16_f32 v185, v196, v197
	global_store_dwordx4 v[186:187], v[182:185], off nt
	v_add_f32_e32 v165, 1.0, v165
	v_rcp_f32_e32 v165, v165
	v_fma_f32 v182, v23, v158, v139
	v_mul_f32_e32 v182, 0xbfb8aa3b, v182
	v_exp_f32_e32 v182, v182
	v_fma_f32 v183, v24, v158, v140
	v_mul_f32_e32 v183, 0xbfb8aa3b, v183
	v_exp_f32_e32 v183, v183
	v_add_f32_e32 v182, 1.0, v182
	v_rcp_f32_e32 v191, v182
	v_mul_f32_e32 v165, v165, v182
	v_fma_f32 v182, v32, v158, v144
	v_mul_f32_e32 v182, 0xbfb8aa3b, v182
	v_exp_f32_e32 v182, v182
	v_add_f32_e32 v183, 1.0, v183
	v_rcp_f32_e32 v192, v183
	v_fma_f32 v184, v25, v158, v141
	v_add_f32_e32 v182, 1.0, v182
	v_rcp_f32_e32 v182, v182
	v_mul_f32_e32 v184, 0xbfb8aa3b, v184
	v_exp_f32_e32 v184, v184
	v_fma_f32 v185, v18, v158, v134
	v_mul_f32_e32 v183, v182, v183
	v_fma_f32 v182, v33, v158, v145
	v_mul_f32_e32 v182, 0xbfb8aa3b, v182
	v_exp_f32_e32 v182, v182
	v_add_f32_e32 v184, 1.0, v184
	v_rcp_f32_e32 v193, v184
; __device__ __forceinline__ unsigned cvt_pk_bf16(float lo, float hi) { unsigned r; asm volatile("v_cvt_pk_bf16_f32 %0, %1, %2" : "=v"(r) : "v"(lo), "v"(hi)); return r; }
;     __device__ __forceinline__ void operator()(const AccT& acc, const Unit& u, int wr, int wc, int fr, int fq) const {
;     ...
;             for (int ai = 0; ai < 2; ++ai)
; #pragma unroll
;                 for (int m = 0; m < 4; ++m) { const int row = row0 + ai * 128 + m * 16;
;                     const float rstd = rs[ai * 4 + m];
;                     f32x4 rt[2], sb[2];
; #pragma unroll
;                     for (int n = 0; n < 2; ++n)
; #pragma unroll
;                         for (int j = 0; j < 4; ++j) { const float ea = __builtin_amdgcn_exp2f(-LOG2E * (acc[ai][0][m][n][j] * rstd + ba[n][j])), eb = __builtin_amdgcn_exp2f(-LOG2E * (acc[ai][1][m][n][j] * rstd + bb[n][j]));
;                             sb[n][j] = __builtin_amdgcn_rcpf(1.0f + eb); rt[n][j] = (1.0f + eb) * __builtin_amdgcn_rcpf(1.0f + ea); }
;                     u32x4 w; w.x = cvt_pk_bf16(rt[0][0], rt[0][1]); w.y = cvt_pk_bf16(rt[0][2], rt[0][3]); w.z = cvt_pk_bf16(rt[1][0], rt[1][1]); w.w = cvt_pk_bf16(rt[1][2], rt[1][3]);
;                     *(u32x4*)(Z + 5 * SEC + (size_t)row * D + ch0) = w;
;                     u32x4 v; v.x = cvt_pk_bf16(sb[0][0], sb[0][1]); v.y = cvt_pk_bf16(sb[0][2], sb[0][3]); v.z = cvt_pk_bf16(sb[1][0], sb[1][1]); v.w = cvt_pk_bf16(sb[1][2], sb[1][3]);
;                     *(u32x4*)(Z + 6 * SEC + (size_t)row * D + ch0) = v; }
;             return;
	v_mul_f32_e32 v185, 0xbfb8aa3b, v185
	v_add_f32_e32 v182, 1.0, v182
	v_rcp_f32_e32 v182, v182
	v_exp_f32_e32 v185, v185
	v_fma_f32 v186, v19, v158, v135
	v_mul_f32_e32 v186, 0xbfb8aa3b, v186
	v_mul_f32_e32 v184, v182, v184
	v_fma_f32 v182, v26, v158, v130
	v_mul_f32_e32 v182, 0xbfb8aa3b, v182
	v_exp_f32_e32 v182, v182
	v_add_f32_e32 v185, 1.0, v185
	v_rcp_f32_e32 v194, v185
	v_exp_f32_e32 v186, v186
	v_add_f32_e32 v182, 1.0, v182
	v_rcp_f32_e32 v182, v182
	v_fma_f32 v187, v20, v158, v136
	v_add_f32_e32 v186, 1.0, v186
	v_rcp_f32_e32 v195, v186
	v_mul_f32_e32 v185, v182, v185
	v_fma_f32 v182, v27, v158, v131
	v_mul_f32_e32 v182, 0xbfb8aa3b, v182
	v_exp_f32_e32 v182, v182
	v_mul_f32_e32 v187, 0xbfb8aa3b, v187
	v_exp_f32_e32 v187, v187
	v_fma_f32 v188, v21, v158, v137
	v_add_f32_e32 v182, 1.0, v182
	v_rcp_f32_e32 v182, v182
	v_add_f32_e32 v187, 1.0, v187
	v_rcp_f32_e32 v196, v187
	v_mul_f32_e32 v188, 0xbfb8aa3b, v188
	v_mul_f32_e32 v186, v182, v186
	v_fma_f32 v182, v28, v158, v132
	v_mul_f32_e32 v182, 0xbfb8aa3b, v182
	v_exp_f32_e32 v182, v182
	v_exp_f32_e32 v188, v188
	v_fma_f32 v138, v6, v159, v138
	v_mul_f32_e32 v138, 0xbfb8aa3b, v138
	v_add_f32_e32 v182, 1.0, v182
	v_rcp_f32_e32 v182, v182
	v_add_f32_e32 v188, 1.0, v188
	v_rcp_f32_e32 v197, v188
	v_exp_f32_e32 v138, v138
	v_mul_f32_e32 v187, v182, v187
	v_fma_f32 v182, v29, v158, v133
	v_mul_f32_e32 v182, 0xbfb8aa3b, v182
	v_exp_f32_e32 v182, v182
	v_add_f32_e32 v138, 1.0, v138
	v_fma_f32 v139, v7, v159, v139
	v_mul_f32_e32 v139, 0xbfb8aa3b, v139
	v_add_f32_e32 v182, 1.0, v182
	v_rcp_f32_e32 v182, v182
	v_exp_f32_e32 v139, v139
	v_fma_f32 v140, v8, v159, v140
	v_mul_f32_e32 v140, 0xbfb8aa3b, v140
	v_mul_f32_e32 v188, v182, v188
	v_cvt_pk_bf16_f32 v182, v0, v165
	v_fma_f32 v0, v14, v159, v142
	v_mul_f32_e32 v0, 0xbfb8aa3b, v0
	v_exp_f32_e32 v0, v0
	v_rcp_f32_e32 v142, v138
	v_add_f32_e32 v139, 1.0, v139
	v_exp_f32_e32 v140, v140
	v_add_f32_e32 v0, 1.0, v0
	v_rcp_f32_e32 v0, v0
	v_fmac_f32_e32 v145, v17, v159
	v_add_f32_e32 v140, 1.0, v140
	v_fma_f32 v130, v10, v159, v130
	v_mul_f32_e32 v0, v0, v138
	v_fma_f32 v138, v15, v159, v143
	v_mul_f32_e32 v138, 0xbfb8aa3b, v138
	v_exp_f32_e32 v138, v138
	v_rcp_f32_e32 v143, v139
	v_mul_f32_e32 v130, 0xbfb8aa3b, v130
	v_exp_f32_e32 v130, v130
	v_add_f32_e32 v138, 1.0, v138
	v_rcp_f32_e32 v138, v138
	v_fmac_f32_e32 v141, v9, v159
	v_fma_f32 v134, v2, v159, v134
	v_mul_f32_e32 v141, 0xbfb8aa3b, v141
	v_mul_f32_e32 v138, v138, v139
	v_fma_f32 v139, v16, v159, v144
	v_mul_f32_e32 v139, 0xbfb8aa3b, v139
	v_exp_f32_e32 v139, v139
	v_rcp_f32_e32 v144, v140
	v_mul_f32_e32 v134, 0xbfb8aa3b, v134
	v_exp_f32_e32 v141, v141
	v_add_f32_e32 v139, 1.0, v139
	v_rcp_f32_e32 v139, v139
	v_exp_f32_e32 v134, v134
	v_add_f32_e32 v130, 1.0, v130
	v_rcp_f32_e32 v130, v130
	v_mul_f32_e32 v139, v139, v140
	v_mul_f32_e32 v140, 0xbfb8aa3b, v145
	v_exp_f32_e32 v140, v140
	v_add_f32_e32 v141, 1.0, v141
	v_add_f32_e32 v134, 1.0, v134
	v_rcp_f32_e32 v145, v141
	v_add_f32_e32 v140, 1.0, v140
	v_rcp_f32_e32 v140, v140
	v_fmac_f32_e32 v133, v13, v159
	v_cvt_pk_bf16_f32 v183, v183, v184
	v_cvt_pk_bf16_f32 v184, v185, v186
	v_mul_f32_e32 v140, v140, v141
	v_rcp_f32_e32 v141, v134
	v_mul_f32_e32 v134, v130, v134
	v_fma_f32 v130, v11, v159, v131
	v_mul_f32_e32 v130, 0xbfb8aa3b, v130
	v_exp_f32_e32 v130, v130
	v_fma_f32 v131, v3, v159, v135
	v_mul_f32_e32 v131, 0xbfb8aa3b, v131
	v_exp_f32_e32 v131, v131
	v_add_f32_e32 v130, 1.0, v130
	v_rcp_f32_e32 v130, v130
	v_cvt_pk_bf16_f32 v185, v187, v188
	v_add_f32_e32 v131, 1.0, v131
	v_rcp_f32_e32 v165, v131
	v_mul_f32_e32 v135, v130, v131
	v_fma_f32 v130, v12, v159, v132
	v_mul_f32_e32 v130, 0xbfb8aa3b, v130
	v_exp_f32_e32 v130, v130
	v_fma_f32 v131, v4, v159, v136
	v_mul_f32_e32 v131, 0xbfb8aa3b, v131
	v_exp_f32_e32 v131, v131
	v_add_f32_e32 v130, 1.0, v130
	v_rcp_f32_e32 v130, v130
	v_lshl_add_u64 v[186:187], v[170:171], 0, s[86:87]
	v_add_f32_e32 v131, 1.0, v131
	v_lshl_add_u64 v[188:189], s[14:15], 0, v[186:187]
	v_mul_f32_e32 v136, v130, v131
	v_mul_f32_e32 v130, 0xbfb8aa3b, v133
	v_exp_f32_e32 v130, v130
	v_lshl_add_u64 v[188:189], v[188:189], 0, v[168:169]
	v_lshl_add_u64 v[186:187], s[18:19], 0, v[186:187]
	global_store_dwordx4 v[188:189], v[182:185], off nt
	v_lshl_add_u64 v[186:187], v[186:187], 0, v[168:169]
	v_fmac_f32_e32 v137, v5, v159
	v_cvt_pk_bf16_f32 v182, v190, v191
	v_cvt_pk_bf16_f32 v183, v192, v193
	v_cvt_pk_bf16_f32 v184, v194, v195
	v_cvt_pk_bf16_f32 v185, v196, v197
	global_store_dwordx4 v[186:187], v[182:185], off nt
	v_add_f32_e32 v130, 1.0, v130
	v_rcp_f32_e32 v130, v130
	v_rcp_f32_e32 v182, v131
	v_mul_f32_e32 v131, 0xbfb8aa3b, v137
	v_exp_f32_e32 v131, v131
	s_nop 0
	v_add_f32_e32 v131, 1.0, v131
	v_rcp_f32_e32 v183, v131
	v_mul_f32_e32 v133, v130, v131
	v_cvt_pk_bf16_f32 v130, v0, v138
	v_cvt_pk_bf16_f32 v131, v139, v140
	v_cvt_pk_bf16_f32 v132, v134, v135
	v_lshl_add_u64 v[134:135], v[170:171], 0, s[94:95]
	v_cvt_pk_bf16_f32 v133, v136, v133
	v_lshl_add_u64 v[136:137], s[14:15], 0, v[134:135]
	v_lshl_add_u64 v[134:135], s[18:19], 0, v[134:135]
	v_lshl_add_u64 v[136:137], v[136:137], 0, v[168:169]
	v_lshl_add_u64 v[134:135], v[134:135], 0, v[168:169]
	global_store_dwordx4 v[136:137], v[130:133], off nt
	s_nop 1
	v_cvt_pk_bf16_f32 v130, v142, v143
	v_cvt_pk_bf16_f32 v131, v144, v145
	v_cvt_pk_bf16_f32 v132, v141, v165
	v_cvt_pk_bf16_f32 v133, v182, v183
	global_store_dwordx4 v[134:135], v[130:133], off nt
